# residual epilogues: first-tile residual loads and gamma/beta fill loads issued together (one exposed round trip instead of two)
# baseline (speedup 1.0000x reference)
; __device__ __forceinline__ int prow0(int pm) { return (pm >> 4) * LP + PADR + (pm & 15) * 256; }
;     __device__ __forceinline__ u32x2 preload_pk(int row, int col) const { return (u32x2){0u, 0u}; }
;     __device__ __forceinline__ u32x2 preload_pk(int row, int col) const { return (u32x2){0u, 0u}; }
;     __device__ __forceinline__ void apply(const RowInfo& ri, const ColInfo& ci, int row, int col, f32x4 a, f32x4 pv, float& s1, float& s2) const {
;         f32x4 h = pv;
;         if (!ident) { const f32x4 gg = *(const f32x4*)(g + col), bb = *(const f32x4*)(b + col); h = (pv - ri.mu) * ri.rstd * gg + bb; }
; template <class Epi>
; __device__ __forceinline__ void gemm_phase(LAS unsigned char* lds, const bf16_t* Ag, const bf16_t* Btg, const int K, const int nM, const int nN, const Epi& E) {
;     ...
;                 if (Epi::PRELOAD && m == 0) {
; #pragma unroll
;                     for (int g2 = 0; g2 < 4; ++g2)
; #pragma unroll
;                         for (int bj = 0; bj < 2; ++bj)
; #pragma unroll
;                             for (int n = 0; n < 2; ++n) pk[g2][bj][n] = E.preload_pk(prow0(pm) + ai * 128 + wr * 64 + g2 * 16 + fr, pn * 256 + bj * 128 + wc * 32 + n * 16 + fq * 4);
;                 }
.LBB0_160:
	v_lshlrev_b64 v[142:143], 2, v[144:145]
	s_and_b64 vcc, exec, s[40:41]
	s_cbranch_vccnz .Lgbh_a
	v_and_b32_e32 v234, 7, v204
	v_bfe_u32 v235, v204, 3, 1
	v_lshrrev_b32_e32 v236, 4, v204
	v_lshlrev_b32_e32 v238, 4, v234
	v_lshl_add_u32 v238, v235, 9, v238
	v_lshlrev_b32_e32 v236, 4, v236
	v_sub_u32_e32 v238, v238, v236
	v_ashrrev_i32_e32 v239, 31, v238
	v_lshl_add_u64 v[240:241], s[24:25], 0, v[142:143]
	v_lshl_add_u64 v[242:243], s[22:23], 0, v[142:143]
	v_lshl_add_u64 v[240:241], v[240:241], 0, v[238:239]
	v_lshl_add_u64 v[242:243], v[242:243], 0, v[238:239]
	global_load_dwordx4 v[244:247], v[240:241], off
	global_load_dwordx4 v[248:251], v[242:243], off
	s_waitcnt vmcnt(2)
	s_branch .Lgbh_b

; __device__ __forceinline__ float bflo(unsigned w) { return __uint_as_float(w << 16); }
; __device__ __forceinline__ float bfhi(unsigned w) { return __uint_as_float(w & 0xffff0000u); }
;     __device__ __forceinline__ void apply(const RowInfo& ri, const ColInfo& ci, int row, int col, f32x4 a, f32x4 pv, float& s1, float& s2) const {
;         f32x4 h = pv;
;         if (!ident) { const f32x4 gg = *(const f32x4*)(g + col), bb = *(const f32x4*)(b + col); h = (pv - ri.mu) * ri.rstd * gg + bb; }
; template <class Epi>
; __device__ __forceinline__ void gemm_phase(LAS unsigned char* lds, const bf16_t* Ag, const bf16_t* Btg, const int K, const int nM, const int nN, const Epi& E) {
;     ...
;                 f32x4 pv[2][2];
; #pragma unroll
;                 for (int bj = 0; bj < 2; ++bj)
; #pragma unroll
;                     for (int n = 0; n < 2; ++n) { const u32x2 w = pk[m][bj][n]; pv[bj][n] = (f32x4){bflo(w.x), bfhi(w.x), bflo(w.y), bfhi(w.y)}; }
;                 const RowInfo ri = E.rowinfo(row, lrow, par, lds);
.Lgbh_b:
	v_lshlrev_b32_e32 v192, 16, v140
	v_and_b32_e32 v193, 0xffff0000, v140
	v_lshlrev_b32_e32 v196, 16, v141
	v_and_b32_e32 v197, 0xffff0000, v141
	v_mov_b32_e32 v183, v182
	s_and_b64 vcc, exec, s[40:41]
	v_lshl_add_u64 v[140:141], s[24:25], 0, v[142:143]
	v_lshl_add_u64 v[142:143], s[22:23], 0, v[142:143]
	s_cbranch_vccnz .Lgbfill_skip1
	v_and_b32_e32 v234, 7, v204
	v_bfe_u32 v235, v204, 3, 1
	v_lshrrev_b32_e32 v236, 4, v204
	v_lshlrev_b32_e32 v238, 4, v234
	v_lshl_add_u32 v238, v235, 9, v238
	v_lshlrev_b32_e32 v236, 4, v236
	v_sub_u32_e32 v238, v238, v236
	v_ashrrev_i32_e32 v239, 31, v238
	v_lshl_add_u64 v[240:241], v[140:141], 0, v[238:239]
	v_lshl_add_u64 v[242:243], v[142:143], 0, v[238:239]
	v_lshrrev_b32_e32 v237, 6, v198
	v_lshlrev_b32_e32 v237, 9, v237
	v_add_u32_e32 v237, 0x21000, v237
	v_add_u32_e32 v238, v237, v236
	v_lshl_add_u32 v237, v235, 7, v237
	v_lshl_add_u32 v237, v234, 4, v237
	s_waitcnt vmcnt(0)
	ds_write_b128 v237, v[244:247]
	ds_write_b128 v237, v[248:251] offset:256
	s_waitcnt lgkmcnt(0)

; __device__ __forceinline__ float bflo(unsigned w) { return __uint_as_float(w << 16); }
; __device__ __forceinline__ float bfhi(unsigned w) { return __uint_as_float(w & 0xffff0000u); }
; __device__ __forceinline__ u32x2 pack4(const f32x4 a) { u32x2 v; v.x = cvt_pk_bf16(a[0], a[1]); v.y = cvt_pk_bf16(a[2], a[3]); return v; }
; __device__ __forceinline__ int prow0(int pm) { return (pm >> 4) * LP + PADR + (pm & 15) * 256; }
;     __device__ __forceinline__ u32x2 preload_pk(int row, int col) const { return (u32x2){0u, 0u}; }
;     __device__ __forceinline__ u32x2 preload_pk(int row, int col) const { return (u32x2){0u, 0u}; }
;     __device__ __forceinline__ void apply(const RowInfo& ri, const ColInfo& ci, int row, int col, f32x4 a, f32x4 pv, float& s1, float& s2) const {
;         f32x4 h = pv;
;         if (!ident) { const f32x4 gg = *(const f32x4*)(g + col), bb = *(const f32x4*)(b + col); h = (pv - ri.mu) * ri.rstd * gg + bb; }
;         const f32x4 v = h * ALPHA + a;
;         *(u32x2*)(xb + (size_t)row * DM + col) = pack4(v);
; template <class Epi>
; __device__ __forceinline__ void gemm_phase(LAS unsigned char* lds, const bf16_t* Ag, const bf16_t* Btg, const int K, const int nM, const int nN, const Epi& E) {
;     ...
;                 if (Epi::PRELOAD && m == 0) {
; #pragma unroll
;                     for (int g2 = 0; g2 < 4; ++g2)
; #pragma unroll
;                         for (int bj = 0; bj < 2; ++bj)
; #pragma unroll
;                             for (int n = 0; n < 2; ++n) pk[g2][bj][n] = E.preload_pk(prow0(pm) + ai * 128 + wr * 64 + g2 * 16 + fr, pn * 256 + bj * 128 + wc * 32 + n * 16 + fq * 4);
;                 }
;                 f32x4 pv[2][2];
; #pragma unroll
;                 for (int bj = 0; bj < 2; ++bj)
; #pragma unroll
;                     for (int n = 0; n < 2; ++n) { const u32x2 w = pk[m][bj][n]; pv[bj][n] = (f32x4){bflo(w.x), bfhi(w.x), bflo(w.y), bfhi(w.y)}; }
;                 const RowInfo ri = E.rowinfo(row, lrow, par, lds);
;                 float s1 = 0.f, s2 = 0.f;
; #pragma unroll
;                 for (int bj = 0; bj < 2; ++bj)
; #pragma unroll
;                     for (int n = 0; n < 2; ++n) E.apply(ri, ci[bj][n], row, pn * 256 + bj * 128 + wc * 32 + n * 16 + fq * 4, acc[ai][bj][m][n], pv[bj][n], s1, s2);
.LBB0_748:
	s_lshr_b32 s12, s74, 4
	s_lshl_b32 s15, s74, 8
	s_mulk_i32 s12, 0x1040
	s_and_b32 s15, s15, 0xf00
	s_add_i32 s15, s15, s12
	s_or_b32 s49, s15, 48
	v_add_u32_e32 v146, s49, v164
	v_lshl_or_b32 v144, s76, 8, v166
	v_ashrrev_i32_e32 v147, 31, v146
	v_ashrrev_i32_e32 v145, 31, v144
	v_lshlrev_b64 v[140:141], 11, v[146:147]
	v_lshlrev_b64 v[148:149], 1, v[144:145]
	v_lshl_add_u64 v[140:141], s[36:37], 0, v[140:141]
	v_lshl_add_u64 v[154:155], v[140:141], 0, v[148:149]
	global_load_dwordx2 v[160:161], v[154:155], off
	global_load_dwordx2 v[162:163], v[154:155], off offset:32
	global_load_dwordx2 v[180:181], v[154:155], off offset:256
	global_load_dwordx2 v[190:191], v[154:155], off offset:288
	v_lshlrev_b64 v[142:143], 2, v[144:145]
	v_lshl_add_u64 v[140:141], s[20:21], 0, v[142:143]
	v_lshl_add_u64 v[142:143], s[22:23], 0, v[142:143]
	v_and_b32_e32 v234, 7, v204
	v_bfe_u32 v235, v204, 3, 1
	v_lshrrev_b32_e32 v236, 4, v204
	v_lshlrev_b32_e32 v238, 4, v234
	v_lshl_add_u32 v238, v235, 9, v238
	v_lshlrev_b32_e32 v236, 4, v236
	v_sub_u32_e32 v238, v238, v236
	v_ashrrev_i32_e32 v239, 31, v238
	v_lshl_add_u64 v[240:241], v[140:141], 0, v[238:239]
	v_lshl_add_u64 v[242:243], v[142:143], 0, v[238:239]
	global_load_dwordx4 v[244:247], v[240:241], off
	global_load_dwordx4 v[248:251], v[242:243], off
	v_lshrrev_b32_e32 v237, 6, v198
	v_lshlrev_b32_e32 v237, 9, v237
	v_add_u32_e32 v237, 0x21000, v237
	v_add_u32_e32 v238, v237, v236
	v_lshl_add_u32 v237, v235, 7, v237
	v_lshl_add_u32 v237, v234, 4, v237
	s_waitcnt vmcnt(0)
	ds_write_b128 v237, v[244:247]
	ds_write_b128 v237, v[248:251] offset:256
	s_waitcnt lgkmcnt(0)
	ds_read_b128 v[150:153], v238
	ds_read_b128 v[156:159], v238 offset:256
	s_add_i32 s12, s14, 0
	s_add_i32 s12, s12, 0x20000
	v_lshl_add_u32 v176, v164, 3, s12
	ds_read_b64 v[188:189], v176
	s_lshl_b32 s52, s76, 2
	s_ashr_i32 s53, s52, 31
	s_or_b64 s[52:53], s[52:53], s[90:91]
	s_waitcnt vmcnt(0) lgkmcnt(0)
	v_lshlrev_b32_e32 v175, 16, v160
	v_and_b32_e32 v160, 0xffff0000, v160
	v_lshlrev_b32_e32 v179, 16, v161
	v_and_b32_e32 v182, 0xffff0000, v161
	s_waitcnt lgkmcnt(0)
	v_sub_f32_e32 v161, v160, v188
	v_sub_f32_e32 v160, v175, v188
	v_sub_f32_e32 v183, v182, v188
	v_sub_f32_e32 v182, v179, v188
	v_pk_mul_f32 v[182:183], v[188:189], v[182:183] op_sel:[1,0]
	v_pk_mul_f32 v[160:161], v[188:189], v[160:161] op_sel:[1,0]
	v_pk_fma_f32 v[152:153], v[152:153], v[182:183], v[158:159]
	v_pk_fma_f32 v[150:151], v[150:151], v[160:161], v[156:157]
	v_pk_fma_f32 v[192:193], v[152:153], s[4:5], v[134:135] op_sel_hi:[1,0,1]
	v_pk_fma_f32 v[194:195], v[150:151], s[4:5], v[132:133] op_sel_hi:[1,0,1]
	v_cvt_pk_bf16_f32 v133, v192, v193
	v_cvt_pk_bf16_f32 v132, v194, v195
	global_store_dwordx2 v[154:155], v[132:133], off
	ds_read_b128 v[132:135], v238 offset:64
	s_nop 0
	ds_read_b128 v[150:153], v238 offset:320
	v_lshlrev_b32_e32 v156, 16, v162
	v_and_b32_e32 v157, 0xffff0000, v162
	v_lshlrev_b32_e32 v158, 16, v163
	v_and_b32_e32 v159, 0xffff0000, v163
	v_sub_f32_e32 v157, v157, v188
	v_sub_f32_e32 v156, v156, v188
	v_sub_f32_e32 v159, v159, v188
	v_sub_f32_e32 v158, v158, v188
	v_pk_mul_f32 v[158:159], v[188:189], v[158:159] op_sel:[1,0]
	v_pk_mul_f32 v[156:157], v[188:189], v[156:157] op_sel:[1,0]
	v_lshlrev_b32_e32 v226, 16, v191
	v_mov_b32_e32 v227, v193
	v_xor_b32_e32 v175, 16, v204
	v_cmp_lt_i32_e32 vcc, v175, v206
	v_xor_b32_e32 v179, 32, v204
	s_waitcnt vmcnt(1) lgkmcnt(0)
	v_pk_fma_f32 v[132:133], v[132:133], v[156:157], v[150:151]
	v_pk_fma_f32 v[134:135], v[134:135], v[158:159], v[152:153]
	v_pk_fma_f32 v[210:211], v[132:133], s[4:5], v[128:129] op_sel_hi:[1,0,1]
	v_pk_fma_f32 v[196:197], v[134:135], s[4:5], v[130:131] op_sel_hi:[1,0,1]
	v_cvt_pk_bf16_f32 v128, v210, v211
	v_cvt_pk_bf16_f32 v129, v196, v197
	global_store_dwordx2 v[154:155], v[128:129], off offset:32
	ds_read_b128 v[128:131], v238 offset:128
	s_nop 0
	ds_read_b128 v[132:135], v238 offset:384
	v_lshlrev_b32_e32 v150, 16, v180
	v_and_b32_e32 v151, 0xffff0000, v180
	v_lshlrev_b32_e32 v152, 16, v181
	v_and_b32_e32 v153, 0xffff0000, v181
	v_sub_f32_e32 v151, v151, v188
	v_sub_f32_e32 v150, v150, v188
	v_sub_f32_e32 v153, v153, v188
	v_sub_f32_e32 v152, v152, v188
	v_pk_mul_f32 v[152:153], v[188:189], v[152:153] op_sel:[1,0]
	v_pk_mul_f32 v[150:151], v[188:189], v[150:151] op_sel:[1,0]
	v_cndmask_b32_e32 v175, v204, v175, vcc
	v_lshlrev_b32_e32 v175, 2, v175
	v_cmp_lt_i32_e32 vcc, v179, v206
	s_waitcnt vmcnt(2) lgkmcnt(0)
; __device__ __forceinline__ float bflo(unsigned w) { return __uint_as_float(w << 16); }
; __device__ __forceinline__ float bfhi(unsigned w) { return __uint_as_float(w & 0xffff0000u); }
; __device__ __forceinline__ u32x2 pack4(const f32x4 a) { u32x2 v; v.x = cvt_pk_bf16(a[0], a[1]); v.y = cvt_pk_bf16(a[2], a[3]); return v; }
;     __device__ __forceinline__ void apply(const RowInfo& ri, const ColInfo& ci, int row, int col, f32x4 a, f32x4 pv, float& s1, float& s2) const {
;         f32x4 h = pv;
;         if (!ident) { const f32x4 gg = *(const f32x4*)(g + col), bb = *(const f32x4*)(b + col); h = (pv - ri.mu) * ri.rstd * gg + bb; }
;         const f32x4 v = h * ALPHA + a;
;         *(u32x2*)(xb + (size_t)row * DM + col) = pack4(v);
;         s1 += (v[0] + v[1]) + (v[2] + v[3]); s2 += (v[0] * v[0] + v[1] * v[1]) + (v[2] * v[2] + v[3] * v[3]);
;     }
; template <class Epi>
; __device__ __forceinline__ void gemm_phase(LAS unsigned char* lds, const bf16_t* Ag, const bf16_t* Btg, const int K, const int nM, const int nN, const Epi& E) {
;     ...
;                 if (Epi::PRELOAD && m == 0) {
; #pragma unroll
;                     for (int g2 = 0; g2 < 4; ++g2)
; #pragma unroll
;                         for (int bj = 0; bj < 2; ++bj)
; #pragma unroll
;                             for (int n = 0; n < 2; ++n) pk[g2][bj][n] = E.preload_pk(prow0(pm) + ai * 128 + wr * 64 + g2 * 16 + fr, pn * 256 + bj * 128 + wc * 32 + n * 16 + fq * 4);
;                 }
;                 f32x4 pv[2][2];
; #pragma unroll
;                 for (int bj = 0; bj < 2; ++bj)
; #pragma unroll
;                     for (int n = 0; n < 2; ++n) { const u32x2 w = pk[m][bj][n]; pv[bj][n] = (f32x4){bflo(w.x), bfhi(w.x), bflo(w.y), bfhi(w.y)}; }
;                 const RowInfo ri = E.rowinfo(row, lrow, par, lds);
;                 float s1 = 0.f, s2 = 0.f;
; #pragma unroll
;                 for (int bj = 0; bj < 2; ++bj)
; #pragma unroll
;                     for (int n = 0; n < 2; ++n) E.apply(ri, ci[bj][n], row, pn * 256 + bj * 128 + wc * 32 + n * 16 + fq * 4, acc[ai][bj][m][n], pv[bj][n], s1, s2);
;                 if (Epi::STATS) {
;                     s1 += __shfl_xor(s1, 16); s1 += __shfl_xor(s1, 32); s2 += __shfl_xor(s2, 16); s2 += __shfl_xor(s2, 32);
;                     if (fq == 0) *(f32x2*)(E.stat_out + ((size_t)row * 16 + pn * 4 + wc) * 2) = (f32x2){s1, s2};
;                 }
	v_pk_fma_f32 v[128:129], v[150:151], v[128:129], v[132:133]
	v_pk_fma_f32 v[130:131], v[152:153], v[130:131], v[134:135]
	v_pk_fma_f32 v[222:223], v[128:129], s[4:5], v[124:125] op_sel_hi:[1,0,1]
	v_pk_fma_f32 v[216:217], v[130:131], s[4:5], v[126:127] op_sel_hi:[1,0,1]
	v_cvt_pk_bf16_f32 v124, v222, v223
	v_cvt_pk_bf16_f32 v125, v216, v217
	global_store_dwordx2 v[154:155], v[124:125], off offset:256
	ds_read_b128 v[180:183], v238 offset:192
	ds_read_b128 v[184:187], v238 offset:448
	v_add_u32_e32 v124, 16, v146
	v_add_u32_e32 v126, 32, v146
	v_add_u32_e32 v128, 48, v146
	v_ashrrev_i32_e32 v125, 31, v124
	v_ashrrev_i32_e32 v127, 31, v126
	v_ashrrev_i32_e32 v129, 31, v128
	v_lshlrev_b64 v[124:125], 11, v[124:125]
	v_lshlrev_b64 v[126:127], 11, v[126:127]
	v_lshlrev_b64 v[128:129], 11, v[128:129]
	v_lshl_add_u64 v[124:125], s[36:37], 0, v[124:125]
	v_lshl_add_u64 v[126:127], s[36:37], 0, v[126:127]
	v_lshl_add_u64 v[128:129], s[36:37], 0, v[128:129]
	v_lshl_add_u64 v[124:125], v[124:125], 0, v[148:149]
	v_lshl_add_u64 v[126:127], v[126:127], 0, v[148:149]
	v_lshl_add_u64 v[224:225], v[128:129], 0, v[148:149]
	global_load_dwordx2 v[162:163], v[124:125], off
	global_load_dwordx2 v[160:161], v[124:125], off offset:32
	global_load_dwordx2 v[158:159], v[124:125], off offset:256
	global_load_dwordx2 v[156:157], v[124:125], off offset:288
	global_load_dwordx2 v[152:153], v[126:127], off
	global_load_dwordx2 v[150:151], v[126:127], off offset:32
	global_load_dwordx2 v[134:135], v[126:127], off offset:256
	global_load_dwordx2 v[132:133], v[126:127], off offset:288
	global_load_dwordx2 v[130:131], v[224:225], off
	global_load_dwordx2 v[128:129], v[224:225], off offset:32
	s_nop 0
	global_load_dwordx2 v[126:127], v[224:225], off offset:256
	global_load_dwordx2 v[124:125], v[224:225], off offset:288
	v_lshlrev_b32_e32 v224, 16, v190
	v_and_b32_e32 v190, 0xffff0000, v190
	v_and_b32_e32 v225, 0xffff0000, v191
	v_sub_f32_e32 v191, v190, v188
	v_sub_f32_e32 v190, v224, v188
	v_sub_f32_e32 v225, v225, v188
	v_sub_f32_e32 v224, v226, v188
	v_pk_mul_f32 v[224:225], v[188:189], v[224:225] op_sel:[1,0]
	v_pk_mul_f32 v[188:189], v[188:189], v[190:191] op_sel:[1,0]
	v_pk_mov_b32 v[190:191], v[194:195], v[192:193] op_sel:[1,0]
	v_mov_b32_e32 v226, v194
	v_pk_mul_f32 v[192:193], v[192:193], v[192:193]
	v_pk_mul_f32 v[194:195], v[194:195], v[194:195]
	v_pk_add_f32 v[190:191], v[190:191], v[226:227]
	v_pk_mov_b32 v[226:227], v[194:195], v[192:193] op_sel:[1,0]
	v_mov_b32_e32 v195, v193
	v_add_f32_e32 v192, v190, v191
	v_pk_add_f32 v[190:191], v[226:227], v[194:195]
	v_pk_mov_b32 v[194:195], v[210:211], v[196:197] op_sel:[1,0]
	v_mov_b32_e32 v226, v210
	v_mov_b32_e32 v227, v197
	v_pk_mul_f32 v[210:211], v[210:211], v[210:211]
	v_pk_mul_f32 v[196:197], v[196:197], v[196:197]
	v_pk_add_f32 v[194:195], v[194:195], v[226:227]
	v_pk_mov_b32 v[226:227], v[210:211], v[196:197] op_sel:[1,0]
	v_mov_b32_e32 v211, v197
	v_pk_add_f32 v[196:197], v[226:227], v[210:211]
	v_pk_add_f32 v[190:191], v[190:191], v[190:191] op_sel_hi:[0,1]
	v_pk_add_f32 v[196:197], v[196:197], v[196:197] op_sel_hi:[0,1]
	v_mul_f32_e32 v190, v222, v222
	v_mul_f32_e32 v196, v216, v216
	v_add_f32_e32 v210, v222, v223
	v_add_f32_e32 v226, v216, v217
	v_pk_fma_f32 v[222:223], v[222:223], v[222:223], v[190:191] op_sel_hi:[1,1,0]
	v_pk_fma_f32 v[216:217], v[216:217], v[216:217], v[196:197] op_sel_hi:[1,1,0]
	v_pk_add_f32 v[194:195], v[194:195], v[194:195] op_sel:[0,1] op_sel_hi:[1,0]
	v_add_f32_e32 v192, 0, v192
	v_cndmask_b32_e32 v179, v204, v179, vcc
	v_lshlrev_b32_e32 v179, 2, v179
	s_waitcnt vmcnt(15) lgkmcnt(0)
	v_pk_fma_f32 v[180:181], v[188:189], v[180:181], v[184:185]
	v_pk_fma_f32 v[182:183], v[224:225], v[182:183], v[186:187]
	v_pk_fma_f32 v[180:181], v[180:181], s[4:5], v[120:121] op_sel_hi:[1,0,1]
	v_pk_fma_f32 v[182:183], v[182:183], s[4:5], v[122:123] op_sel_hi:[1,0,1]
	v_mov_b32_e32 v222, v180
	v_mov_b32_e32 v216, v181
	v_mov_b32_e32 v196, v182
	v_mov_b32_e32 v190, v183
	v_mul_f32_e32 v211, v180, v180
	v_mul_f32_e32 v227, v181, v181
	v_mul_f32_e32 v195, v182, v182
	v_mul_f32_e32 v193, v183, v183
	v_pk_add_f32 v[120:121], v[222:223], v[216:217]
	v_pk_add_f32 v[122:123], v[196:197], v[190:191]
	v_pk_add_f32 v[184:185], v[210:211], v[226:227]
	v_pk_add_f32 v[120:121], v[120:121], v[122:123]
	v_pk_add_f32 v[122:123], v[194:195], v[192:193]
	v_cvt_pk_bf16_f32 v180, v180, v181
	v_pk_add_f32 v[122:123], v[184:185], v[122:123]
	v_cvt_pk_bf16_f32 v181, v182, v183
	v_pk_add_f32 v[120:121], v[120:121], v[122:123]
	ds_bpermute_b32 v122, v175, v120
	ds_bpermute_b32 v123, v175, v121
	global_store_dwordx2 v[154:155], v[180:181], off offset:288
	s_waitcnt lgkmcnt(0)
	v_pk_add_f32 v[120:121], v[120:121], v[122:123]
	ds_bpermute_b32 v122, v179, v120
	ds_bpermute_b32 v123, v179, v121
	s_and_saveexec_b64 s[14:15], s[44:45]
	s_cbranch_execz .LBB0_750
	s_waitcnt lgkmcnt(0)
	v_pk_add_f32 v[120:121], v[120:121], v[122:123]
	v_lshlrev_b64 v[122:123], 7, v[146:147]
	v_lshl_add_u64 v[122:123], s[34:35], 0, v[122:123]
	v_lshl_add_u64 v[122:123], s[52:53], 3, v[122:123]
	global_store_dwordx2 v[122:123], v[120:121], off
